# v28 + generation guard kept off the critical path (release word re-read next to the ticket prefetch; barrier arrive spins only if the skipped round is still pending)
# baseline (speedup 1.0000x reference)
; #define LAS __attribute__((address_space(3)))
; __global__ __launch_bounds__(512, 2) void hybrid_fwd(Params P0) {
;     extern __shared__ __attribute__((aligned(16))) unsigned char shm[];
;     LAS unsigned char* lds = (LAS unsigned char*)shm;
;     cg::grid_group grid = cg::this_grid();
;     volatile LAS unsigned* xst = (volatile LAS unsigned*)(lds + 139248);
;     if (threadIdx.x == 0) { xst[0] = 0u; xst[1] = 0u; }
;     __syncthreads();
;     XcdBarrier xb = xcd_barrier_post((unsigned*)(P0.ws + WS_END), xst);
_Z10hybrid_fwd6Params:
	v_mov_b32_e32 v250, -1
	v_mov_b32_e32 v251, -2
	s_load_dwordx8 s[20:27], s[0:1], 0x40
	s_add_u32 s86, s0, 0x58
	s_addc_u32 s87, s1, 0
	v_and_b32_e32 v155, 0x3ff, v0
	v_cmp_eq_u32_e64 s[6:7], 0, v155
	s_mov_b64 s[4:5], exec
	s_nop 0
	v_writelane_b32 v249, s6, 0
	s_nop 1
	v_writelane_b32 v249, s7, 1
	s_and_b64 s[6:7], s[4:5], s[6:7]
	s_mov_b64 exec, s[6:7]
	s_cbranch_execz .LBB0_2
	s_add_i32 s3, 0, 0x21ff0
	v_mov_b32_e32 v1, 0
	v_mov_b32_e32 v2, s3
	s_add_i32 s3, 0, 0x21ff4
	ds_write_b32 v2, v1
	v_mov_b32_e32 v2, s3
	ds_write_b32 v2, v1

; __device__ __forceinline__ unsigned xb_add(unsigned* p, unsigned v) { return __hip_atomic_fetch_add(p, v, __ATOMIC_RELAXED, __HIP_MEMORY_SCOPE_AGENT); }
; __device__ __forceinline__ void xcd_barrier(const XcdBarrier& b) {
;     ...
;         unsigned nloc = b.st[0], nx = b.st[1];
;         if (nloc == 0u) { xcd_barrier_complete(bar, b.x, nloc, nx); b.st[0] = nloc; b.st[1] = nx; }
;         const unsigned old = xb_add(&bar[XB_XSUB(b.x)], 1u);
.LBB0_38:
	v_cmp_ne_u32_e32 vcc, -1, v250
	s_nop 4
	s_cbranch_vccz .Lgw_done
	v_readlane_b32 s6, v248, 8
	v_readlane_b32 s7, v248, 9
.Lgw_spin:
	s_nop 4
	global_load_dword v3, v137, s[6:7] sc1
	s_waitcnt vmcnt(0)
	v_cmp_eq_u32_e32 vcc, v3, v250
	s_nop 4
	s_cbranch_vccz .Lgw_ok
	s_sleep 1
	s_branch .Lgw_spin
.Lgw_ok:
	v_mov_b32_e32 v250, -1

; __device__ __forceinline__ unsigned xb_ld(unsigned* p)              { return __hip_atomic_load(p, __ATOMIC_RELAXED, __HIP_MEMORY_SCOPE_AGENT); }
; __device__ __forceinline__ unsigned xb_add(unsigned* p, unsigned v) { return __hip_atomic_fetch_add(p, v, __ATOMIC_RELAXED, __HIP_MEMORY_SCOPE_AGENT); }
; #define XB_SPIN(cond, bar) do { unsigned _sp = 0; while (cond) { __builtin_amdgcn_s_sleep(1); \
;     if ((++_sp & 255u) == 0u) { if (xb_ld(&(bar)[XB_TMO])) break; if (_sp > XB_SPIN_CAP) { atomicAdd(&(bar)[XB_TMO], 1u); break; } } } } while (0)
; __device__ __forceinline__ void xcd_barrier(const XcdBarrier& b) {
;     ...
;         const unsigned old = xb_add(&bar[XB_XSUB(b.x)], 1u);
;         const unsigned gen = old / nloc;
;         if (old + 1u == (gen + 1u) * nloc) {
;             __builtin_amdgcn_fence(__ATOMIC_RELEASE, "agent");
;             asm volatile("s_waitcnt vmcnt(0)" ::: "memory");
;             const unsigned og = xb_add(&bar[XB_TOP], 1u);
;             const unsigned tg = og / nx;
;             if (og + 1u == (tg + 1u) * nx) xb_add(&bar[XB_TOPGEN], 1u);
;             else XB_SPIN(xb_ld(&bar[XB_TOPGEN]) == tg, bar);
;             __builtin_amdgcn_fence(__ATOMIC_ACQUIRE, "agent");
;             xb_add(&bar[XB_XGEN(b.x)], 1u);
;             asm volatile("s_waitcnt vmcnt(0)" ::: "memory");
;         } else {
;             XB_SPIN(xb_ld(&bar[XB_XGEN(b.x)]) == gen, bar);
.Lskipw_chk:
	v_readlane_b32 s6, v248, 59
	s_cmp_lt_u32 s6, 0x88
	s_cbranch_scc1 .Lskipw_no
	v_mov_b32_e32 v250, v1
	v_mov_b32_e32 v251, -2
	s_branch .LBB0_54

; __device__ __forceinline__ float rcp_f(float v) { return __builtin_amdgcn_rcpf(v); }
; __device__ __forceinline__ void b_item(const Params& P, int layer, LAS unsigned char* lds, int item, int tid) {
;     ...
;     for (int u = 0; u < 2; ++u) {
;         float l = lrun[u]; l += __shfl_xor(l, 16); l += __shfl_xor(l, 32);
;         const float inv = rcp_f(l);
;         const size_t tok = tok0 + 64 * qc + 32 * th + 16 * u + c15;
;         const bf16_t* gate = pjp(proj, BG, 128, h, tok);
;         bf16_t* y = (bf16_t*)(P.ws + (layer == 0 ? WS_H : WS_D1)) + tok * DM + YB + h * 128;
; __global__ __launch_bounds__(512, 2) void hybrid_fwd(Params P0) {
;     ...
;                     if (tid == 0) *sit = (int)atomicAdd(ctr, 1u);
.Lepi_A:
	v_lshl_add_u64 v[64:65], s[50:51], 0, v[152:153]
	v_or_b32_e32 v64, v64, v154
	v_lshl_add_u64 v[66:67], v[64:65], 0, s[12:13]
	v_lshlrev_b64 v[66:67], 8, v[66:67]
	v_lshl_add_u64 v[70:71], v[156:157], 0, v[66:67]
	s_and_saveexec_b64 s[14:15], s[40:41]
	s_cbranch_execz .Lbq_ep_skip
	v_mov_b32_e32 v246, 1
	global_atomic_add v246, v137, v246, s[48:49] sc0
	v_readlane_b32 vcc_lo, v248, 8
	v_readlane_b32 vcc_hi, v248, 9
	s_nop 4
	global_load_dword v251, v137, vcc sc1

; __global__ __launch_bounds__(512, 2) void hybrid_fwd(Params P0) {
;     ...
;                     if (tid == 0) *sit = (int)atomicAdd(ctr, 1u);
;                     __syncthreads();
;                     const int it = *sit;
;                     __syncthreads();
.LBB0_142:
	s_and_saveexec_b64 s[0:1], s[40:41]
	s_cbranch_execz .LBB0_146
	s_waitcnt vmcnt(16)
	v_cmp_ne_u32_e32 vcc, -1, v250
	s_nop 4
	s_cbranch_vccz .Lgq_done
	v_cmp_ne_u32_e32 vcc, -2, v251
	s_nop 4
	s_cbranch_vccz .Lgq_done
	v_cmp_ne_u32_e32 vcc, v251, v250
	s_nop 4
	s_cbranch_vccz .Lgq_done
	v_mov_b32_e32 v250, -1
.Lgq_done:
	v_mov_b32_e32 v1, s79
	ds_write_b32 v1, v246
